# P0 tail: rel-bias table (7 serial gather iterations on workgroup 0) split one iteration each over workgroups 0,2..7
# speedup vs baseline: 1.0017x; 1.0017x over previous
; __global__ void __launch_bounds__(512, 2) mk_fwd(Args args) {
;     ...
;         if (bxp == 0) { const float* rb = args.in[2]; float* BIAS = PF32(WS_BIAS);
;             for (int i = tid; i < 3 * NH * 129; i += 512) { const int g = i / (NH * 129), h = (i / 129) % NH, dist = i % 129; BIAS[i] = rb[rel_bucket(dist << (2 * g)) * NH + h] * LOG2E; } }
;         if (bxp == 1) { const float* lam = args.in[20]; float* SP8 = PF32(WS_SP8);
;             for (int i = tid; i < D; i += 512) SP8[i] = 8.0f * log1pf(expf(-lam[i])); }
.LBB0_182:
	s_or_b64 exec, exec, s[16:17]
	s_cmp_eq_u32 s58, 1
	s_cbranch_scc1 .Lp0_sp8
	s_cmp_gt_u32 s58, 7
	s_cbranch_scc1 .LBB0_197
	s_max_u32 s2, s58, 1
	s_add_i32 s2, s2, -1
	s_lshl_b32 s2, s2, 9
	v_add_u32_e32 v108, s2, v108
	s_branch .Lp0_bias
.Lp0_sp8:
	s_movk_i32 s2, 0x400
	v_cmp_gt_i32_e32 vcc, s2, v108
	s_and_saveexec_b64 s[2:3], vcc
	s_cbranch_execz .LBB0_187
	s_load_dwordx2 s[4:5], s[0:1], 0xa0
	v_ashrrev_i32_e32 v109, 31, v108
	v_lshlrev_b64 v[0:1], 2, v[108:109]
	v_lshl_add_u64 v[2:3], s[14:15], 0, v[0:1]
	s_waitcnt vmcnt(6)
	v_add_u32_e32 v6, 0xfffffe00, v108
	s_waitcnt lgkmcnt(0)
	v_lshl_add_u64 v[0:1], s[4:5], 0, v[0:1]
	s_mov_b64 s[4:5], 0x1fa10000
	v_lshl_add_u64 v[2:3], v[2:3], 0, s[4:5]
	s_mov_b64 s[4:5], 0
	s_mov_b32 s8, 0xbfb8aa3b
	s_mov_b32 s9, 0x42ce8ed0
	s_mov_b32 s10, 0xc2b17218
	s_mov_b32 s11, 0x7f800000
	v_mov_b32_e32 v7, 0x7f800000
	s_mov_b32 s12, 0x3f2aaaab
	s_waitcnt vmcnt(5)
	v_mov_b32_e32 v8, 0x3ecc95a3
	s_mov_b32 s13, 0x3f317218
	s_mov_b32 s16, 0x33800000
	s_mov_b64 s[6:7], 0x800
	s_movk_i32 s17, 0x1ff
	v_mov_b32_e32 v4, 0x3f317218

; __global__ void __launch_bounds__(512, 2) mk_fwd(Args args) {
;     ...
;         if (bxp == 0) { const float* rb = args.in[2]; float* BIAS = PF32(WS_BIAS);
;             for (int i = tid; i < 3 * NH * 129; i += 512) { const int g = i / (NH * 129), h = (i / 129) % NH, dist = i % 129; BIAS[i] = rb[rel_bucket(dist << (2 * g)) * NH + h] * LOG2E; } }
.Lp0_bias:
	s_movk_i32 s2, 0xc18
	v_cmp_gt_i32_e32 vcc, s2, v108
	s_and_saveexec_b64 s[2:3], vcc
	s_cbranch_execz .LBB0_196
	s_load_dwordx2 s[4:5], s[0:1], 0x10
	v_ashrrev_i32_e32 v109, 31, v108
	v_lshl_add_u64 v[0:1], v[108:109], 2, s[14:15]
	s_mov_b64 s[6:7], 0x1fa00000
	v_lshl_add_u64 v[0:1], v[0:1], 0, s[6:7]
	s_mov_b64 s[6:7], 0
	s_mov_b32 s12, 0xfe03f81
	s_movk_i32 s13, 0xff7f
	s_mov_b32 s14, 0x800000
	s_mov_b32 s15, 0x3f317217
	s_mov_b32 s16, 0x7f800000
	s_mov_b32 s17, 0x409b43d5
	s_mov_b64 s[8:9], 0x800
	s_movk_i32 s18, -1
	v_mov_b32_e32 v2, 0x41b17218
	s_branch .LBB0_194
